# weight-conversion items dealt wave-major so the leftover round spreads over 128 workgroups
# baseline (speedup 1.0000x reference)
; __device__ __forceinline__ void ph_cvt_norm1(unsigned char* smem, int li) {
;     ...
;     const int I1 = 16 * (nq / 32), I2 = (ko / 64) * 32, I3 = 16 * (5632 / 32), I4 = 44 * 32;
;     for (int it = gw; it < I1 + I2 + I3 + I4; it += NGW) {
.LBB0_1056:
	s_lshr_b32 s53, s51, 1
	s_lshr_b32 s54, s50, 1
	s_ashr_i32 s2, s5, 6
	s_lshl_b32 s3, s6, 3
	s_add_i32 s55, s53, s54
	v_and_b32_e32 v5, 63, v1
	s_add_i32 s18, s3, s2
	s_mul_i32 s98, s2, s4
	s_add_i32 s98, s98, s6

; __device__ __forceinline__ void cvt_item(const float* __restrict__ W, int K, int N, bf16_t* WT, float* scr, int item, int lane, int lim, int grp, int P) {
;     const int nblk = N / 32, kb = item / nblk, nb = item - kb * nblk, k0 = 64 * kb, n0 = 32 * nb;
;     const int sc = srccol(n0 + (lane & 31), lim, grp, P);
; __device__ __forceinline__ void ph_cvt_norm1(unsigned char* smem, int li) {
;     ...
;     for (int it = gw; it < I1 + I2 + I3 + I4; it += NGW) {
	s_lshl_b32 s38, s4, 3
	s_addk_i32 s55, 0x1080
	s_cmp_ge_i32 s18, s55
	v_lshlrev_b32_e32 v0, 3, v5
	s_cbranch_scc1 .LBB0_1085
	s_mulk_i32 s2, 0x2100
	v_and_b32_e32 v17, 31, v1
	v_lshrrev_b32_e32 v18, 3, v5
	v_and_b32_e32 v1, 56, v0
	s_add_i32 s4, s2, 0
	v_mul_u32_u24_e32 v3, 0x84, v1
	v_lshlrev_b32_e32 v180, 1, v1
	v_lshlrev_b32_e32 v1, 2, v18
	s_lshr_b32 s56, s51, 5
	v_add3_u32 v19, s4, v3, v1
	v_cvt_f32_ubyte0_e32 v1, s56
	v_rcp_iflag_f32_e32 v3, v1
	v_cvt_f32_u32_e32 v14, s39
	s_waitcnt lgkmcnt(0)
	v_lshl_add_u64 v[6:7], s[42:43], 0, v[180:181]
	s_mov_b64 s[2:3], 0x1b00000
	v_mul_f32_e32 v3, 0x4f7ffffe, v3
	v_cvt_u32_f32_e32 v3, v3
	v_rcp_iflag_f32_e32 v14, v14
	v_lshl_add_u64 v[8:9], v[6:7], 0, s[2:3]
	s_mov_b64 s[2:3], 0x1000000
	v_lshl_add_u64 v[10:11], v[6:7], 0, s[2:3]
	s_mov_b64 s[2:3], 0xc00000
	v_lshl_add_u64 v[12:13], v[6:7], 0, s[2:3]
	v_readfirstlane_b32 s3, v3
	v_mul_f32_e32 v3, 0x4f7ffffe, v14
	s_sub_i32 s2, 0, s56
	v_cvt_u32_f32_e32 v3, v3
	s_mul_i32 s2, s2, s3
	s_mul_hi_u32 s2, s3, s2
	s_add_i32 s58, s3, s2
	s_sub_i32 s2, 0, s39
	v_mul_lo_u32 v14, s2, v3
	v_lshrrev_b32_e32 v2, 5, v5
	v_mul_hi_u32 v14, v3, v14
	v_lshl_add_u32 v4, v17, 2, s4
	v_or_b32_e32 v20, 8, v18
	v_or_b32_e32 v21, 16, v18
	v_or_b32_e32 v22, 24, v18
	v_mov_b32_e32 v1, v2
	s_mov_b32 s57, s51
	v_add_u32_e32 v23, v3, v14
	s_mov_b32 s59, s98
	s_branch .LBB0_1060
